# P5: x1 read once: 4 waves split each 16-row group by 256-col k-blocks, partial logits/ssq exchanged via LDS, H2 written from kept registers (no second read)
# speedup vs baseline: 1.0177x; 1.0101x over previous
.LBB0_777:
	s_waitcnt vmcnt(0)
	v_lshlrev_b32_e32 v228, 4, v192
	v_add_u32_e32 v228, 0x10800, v228
	ds_write_b64 v228, v[102:103] offset:0
	ds_write_b64 v228, v[100:101] offset:8
	ds_write_b64 v228, v[106:107] offset:1024
	ds_write_b64 v228, v[104:105] offset:1032
	ds_write_b64 v228, v[110:111] offset:2048
	ds_write_b64 v228, v[108:109] offset:2056
	ds_write_b64 v228, v[114:115] offset:3072
	ds_write_b64 v228, v[112:113] offset:3080
	ds_write_b128 v228, v[8:11] offset:4096
	ds_write_b128 v228, v[0:3] offset:5120
	ds_write_b128 v228, v[4:7] offset:6144
	ds_write_b128 v228, v[12:15] offset:7168
	s_lshr_b32 s101, s61, 1
	s_and_b32 s99, s101, 3
	s_lshr_b32 s100, s101, 2
	s_mov_b32 s98, 0
	v_lshrrev_b32_e32 v229, 4, v192
	s_lshl_b32 s101, s99, 10
	v_lshl_add_u32 v230, v229, 5, s101
	v_add_u32_e32 v230, 0x10800, v230
	s_lshl_b32 s101, s100, 2
	s_add_i32 s101, s101, s99
	s_mulk_i32 s101, 0x500
	v_lshl_add_u32 v231, v192, 4, s101
	v_add_u32_e32 v231, 0x14000, v231
	v_lshl_add_u32 v232, v192, 2, s101
	v_add_u32_e32 v232, 0x14400, v232
	s_mul_i32 s101, s100, 0x1400
	v_lshl_add_u32 v233, v192, 4, s101
	v_add_u32_e32 v233, 0x14000, v233
	v_lshl_add_u32 v234, v192, 2, s101
	v_add_u32_e32 v234, 0x14400, v234
	s_lshl_b32 s101, s99, 9
	v_lshl_add_u32 v240, v229, 4, s101
	v_add_u32_e32 v240, 0x6e00000, v240
	v_mov_b32_e32 v241, 0
	s_waitcnt lgkmcnt(0)
.Lp5n_loop:
	s_and_b32 s51, s98, 1
	s_and_b32 s101, s98, 6
	s_lshl_b32 s61, s100, 3
	s_add_i32 s61, s61, s101
	s_lshl_b32 s62, s61, 4
	s_lshl_b32 s101, s94, 8
	s_add_i32 s62, s62, s101
	v_or_b32_e32 v130, s62, v120
	s_lshl_b32 s50, s51, 4
	v_add_u32_e32 v16, s50, v130
	v_ashrrev_i32_e32 v17, 31, v16
	v_lshlrev_b64 v[16:17], 12, v[16:17]
	v_mov_b32_e32 v135, 0
	v_lshl_add_u64 v[118:119], v[96:97], 0, v[16:17]
	v_mov_b32_e32 v16, 0
	v_mov_b32_e32 v17, v135
	v_mov_b32_e32 v18, v135
	v_mov_b32_e32 v19, v135
	s_lshl_b32 s0, s99, 10
	s_mov_b32 s1, 0
	s_lshl_b32 s101, s99, 13
	v_add_u32_e32 v84, s101, v129
	v_lshl_add_u64 v[236:237], v[118:119], 0, s[0:1]
	global_load_dwordx4 v[148:151], v[236:237], off offset:16
	global_load_dwordx4 v[152:155], v[236:237], off
	global_load_dwordx4 v[156:159], v[236:237], off offset:144
	global_load_dwordx4 v[160:163], v[236:237], off offset:128
	global_load_dwordx4 v[164:167], v[236:237], off offset:272
	global_load_dwordx4 v[168:171], v[236:237], off offset:256
	global_load_dwordx4 v[172:175], v[236:237], off offset:400
	global_load_dwordx4 v[176:179], v[236:237], off offset:384
	global_load_dwordx4 v[196:199], v[236:237], off offset:528
	global_load_dwordx4 v[200:203], v[236:237], off offset:512
	global_load_dwordx4 v[204:207], v[236:237], off offset:656
	global_load_dwordx4 v[208:211], v[236:237], off offset:640
	global_load_dwordx4 v[212:215], v[236:237], off offset:768
	global_load_dwordx4 v[216:219], v[236:237], off offset:784
	global_load_dwordx4 v[220:223], v[236:237], off offset:912
	global_load_dwordx4 v[224:227], v[236:237], off offset:896
	v_add_u32_e32 v238, s50, v130
	v_ashrrev_i32_e32 v239, 31, v238
	v_lshlrev_b64 v[238:239], 11, v[238:239]
	v_lshl_add_u64 v[238:239], s[78:79], 0, v[238:239]
	v_lshl_add_u64 v[238:239], v[238:239], 0, v[240:241]
	s_waitcnt vmcnt(0)
	v_mov_b64_e32 v[80:81], v[148:149]
	v_mov_b64_e32 v[82:83], v[150:151]
	v_mov_b64_e32 v[136:137], v[152:153]
	v_mov_b64_e32 v[138:139], v[154:155]
	v_mov_b64_e32 v[68:69], v[156:157]
	v_mov_b64_e32 v[70:71], v[158:159]
	v_mov_b64_e32 v[72:73], v[160:161]
	v_mov_b64_e32 v[74:75], v[162:163]
	v_mov_b64_e32 v[60:61], v[164:165]
	v_mov_b64_e32 v[62:63], v[166:167]
	v_mov_b64_e32 v[64:65], v[168:169]
	v_mov_b64_e32 v[66:67], v[170:171]
	v_mov_b64_e32 v[52:53], v[172:173]
	v_mov_b64_e32 v[54:55], v[174:175]
	v_mov_b64_e32 v[56:57], v[176:177]
	v_mov_b64_e32 v[58:59], v[178:179]
	v_mov_b64_e32 v[44:45], v[196:197]
	v_mov_b64_e32 v[46:47], v[198:199]
	v_mov_b64_e32 v[48:49], v[200:201]
	v_mov_b64_e32 v[50:51], v[202:203]
	v_mov_b64_e32 v[36:37], v[204:205]
	v_mov_b64_e32 v[38:39], v[206:207]
	v_mov_b64_e32 v[40:41], v[208:209]
	v_mov_b64_e32 v[42:43], v[210:211]
	v_mov_b64_e32 v[32:33], v[212:213]
	v_mov_b64_e32 v[34:35], v[214:215]
	v_mov_b64_e32 v[28:29], v[216:217]
	v_mov_b64_e32 v[30:31], v[218:219]
	v_mov_b64_e32 v[20:21], v[220:221]
	v_mov_b64_e32 v[22:23], v[222:223]
	v_mov_b64_e32 v[24:25], v[224:225]
	v_mov_b64_e32 v[26:27], v[226:227]
	v_cvt_pk_bf16_f32 v78, v80, v81
	v_fmac_f32_e32 v135, v136, v136
	v_fmac_f32_e32 v135, v137, v137
	v_fmac_f32_e32 v135, v138, v138
	v_cvt_pk_bf16_f32 v76, v136, v137
	v_cvt_pk_bf16_f32 v77, v138, v139
	v_fmac_f32_e32 v135, v139, v139
	v_lshlrev_b32_e32 v140, 16, v76
	v_and_b32_e32 v141, 0xffff0000, v76
	v_lshlrev_b32_e32 v142, 16, v77
	v_and_b32_e32 v143, 0xffff0000, v77
	v_lshlrev_b32_e32 v144, 16, v78
	v_and_b32_e32 v145, 0xffff0000, v78
	v_sub_f32_e32 v140, v136, v140
	v_sub_f32_e32 v141, v137, v141
	v_sub_f32_e32 v142, v138, v142
	v_sub_f32_e32 v143, v139, v143
	v_fmac_f32_e32 v135, v80, v80
	v_sub_f32_e32 v144, v80, v144
	v_sub_f32_e32 v145, v81, v145
	v_fmac_f32_e32 v135, v81, v81
	v_cvt_pk_bf16_f32 v80, v140, v141
	v_cvt_pk_bf16_f32 v81, v142, v143
	ds_read_b128 v[136:139], v84
	ds_read_b128 v[140:143], v84 offset:32768
	v_cvt_pk_bf16_f32 v79, v82, v83
	v_fmac_f32_e32 v135, v82, v82
	s_waitcnt lgkmcnt(1)
	v_mfma_f32_16x16x32_bf16 v[16:19], v[76:79], v[136:139], v[16:19]
	v_lshlrev_b32_e32 v146, 16, v79
	v_and_b32_e32 v147, 0xffff0000, v79
	v_sub_f32_e32 v146, v82, v146
	v_sub_f32_e32 v147, v83, v147
	v_fmac_f32_e32 v135, v83, v83
	v_cvt_pk_bf16_f32 v82, v144, v145
	v_cvt_pk_bf16_f32 v83, v146, v147
	v_fmac_f32_e32 v135, v72, v72
	v_mfma_f32_16x16x32_bf16 v[16:19], v[80:83], v[136:139], v[16:19]
	v_fmac_f32_e32 v135, v73, v73
	v_fmac_f32_e32 v135, v74, v74
	v_fmac_f32_e32 v135, v75, v75
	s_waitcnt lgkmcnt(0)
	v_mfma_f32_16x16x32_bf16 v[16:19], v[76:79], v[140:143], v[16:19]
	v_cvt_pk_bf16_f32 v76, v72, v73
	v_cvt_pk_bf16_f32 v77, v74, v75
	v_cvt_pk_bf16_f32 v78, v68, v69
	v_fmac_f32_e32 v135, v68, v68
	v_lshlrev_b32_e32 v80, 16, v76
	v_and_b32_e32 v81, 0xffff0000, v76
	v_lshlrev_b32_e32 v82, 16, v77
	v_and_b32_e32 v83, 0xffff0000, v77
	v_lshlrev_b32_e32 v136, 16, v78
	v_and_b32_e32 v137, 0xffff0000, v78
	v_sub_f32_e32 v80, v72, v80
	v_sub_f32_e32 v81, v73, v81
	v_sub_f32_e32 v82, v74, v82
	v_sub_f32_e32 v83, v75, v83
	v_sub_f32_e32 v136, v68, v136
	v_sub_f32_e32 v137, v69, v137
	v_fmac_f32_e32 v135, v69, v69
	v_cvt_pk_bf16_f32 v68, v80, v81
	v_cvt_pk_bf16_f32 v69, v82, v83
	ds_read_b128 v[72:75], v84 offset:1024
	ds_read_b128 v[80:83], v84 offset:33792
	v_cvt_pk_bf16_f32 v79, v70, v71
	v_fmac_f32_e32 v135, v70, v70
	s_waitcnt lgkmcnt(1)
	v_mfma_f32_16x16x32_bf16 v[16:19], v[76:79], v[72:75], v[16:19]
	v_lshlrev_b32_e32 v138, 16, v79
	v_and_b32_e32 v139, 0xffff0000, v79
	v_fmac_f32_e32 v135, v71, v71
	v_sub_f32_e32 v138, v70, v138
	v_sub_f32_e32 v139, v71, v139
	v_cvt_pk_bf16_f32 v70, v136, v137
	v_cvt_pk_bf16_f32 v71, v138, v139
	v_fmac_f32_e32 v135, v64, v64
	v_mfma_f32_16x16x32_bf16 v[16:19], v[68:71], v[72:75], v[16:19]
	v_fmac_f32_e32 v135, v65, v65
	v_fmac_f32_e32 v135, v66, v66
	v_cvt_pk_bf16_f32 v68, v64, v65
	v_cvt_pk_bf16_f32 v69, v66, v67
	v_fmac_f32_e32 v135, v67, v67
	v_lshlrev_b32_e32 v72, 16, v68
	v_and_b32_e32 v73, 0xffff0000, v68
	v_lshlrev_b32_e32 v74, 16, v69
	v_and_b32_e32 v75, 0xffff0000, v69
	s_waitcnt lgkmcnt(0)
	v_mfma_f32_16x16x32_bf16 v[16:19], v[76:79], v[80:83], v[16:19]
	v_cvt_pk_bf16_f32 v70, v60, v61
	v_sub_f32_e32 v72, v64, v72
	v_lshlrev_b32_e32 v76, 16, v70
	v_and_b32_e32 v77, 0xffff0000, v70
	v_sub_f32_e32 v73, v65, v73
	v_sub_f32_e32 v74, v66, v74
	v_sub_f32_e32 v75, v67, v75
	v_fmac_f32_e32 v135, v60, v60
	v_sub_f32_e32 v76, v60, v76
	v_sub_f32_e32 v77, v61, v77
	v_fmac_f32_e32 v135, v61, v61
	v_cvt_pk_bf16_f32 v60, v72, v73
	v_cvt_pk_bf16_f32 v61, v74, v75
	ds_read_b128 v[64:67], v84 offset:2048
	ds_read_b128 v[72:75], v84 offset:34816
	v_cvt_pk_bf16_f32 v71, v62, v63
	v_fmac_f32_e32 v135, v62, v62
	s_waitcnt lgkmcnt(1)
	v_mfma_f32_16x16x32_bf16 v[16:19], v[68:71], v[64:67], v[16:19]
	v_lshlrev_b32_e32 v78, 16, v71
	v_and_b32_e32 v79, 0xffff0000, v71
	v_fmac_f32_e32 v135, v63, v63
	v_sub_f32_e32 v78, v62, v78
	v_sub_f32_e32 v79, v63, v79
	v_cvt_pk_bf16_f32 v62, v76, v77
	v_cvt_pk_bf16_f32 v63, v78, v79
	v_fmac_f32_e32 v135, v56, v56
	v_mfma_f32_16x16x32_bf16 v[16:19], v[60:63], v[64:67], v[16:19]
	v_fmac_f32_e32 v135, v57, v57
	v_fmac_f32_e32 v135, v58, v58
	v_cvt_pk_bf16_f32 v60, v56, v57
	v_cvt_pk_bf16_f32 v61, v58, v59
	v_fmac_f32_e32 v135, v59, v59
	v_lshlrev_b32_e32 v64, 16, v60
	v_and_b32_e32 v65, 0xffff0000, v60
	v_lshlrev_b32_e32 v66, 16, v61
	v_and_b32_e32 v67, 0xffff0000, v61
	s_waitcnt lgkmcnt(0)
	v_mfma_f32_16x16x32_bf16 v[16:19], v[68:71], v[72:75], v[16:19]
	v_cvt_pk_bf16_f32 v62, v52, v53
	v_sub_f32_e32 v64, v56, v64
	v_lshlrev_b32_e32 v68, 16, v62
	v_and_b32_e32 v69, 0xffff0000, v62
	v_sub_f32_e32 v65, v57, v65
	v_sub_f32_e32 v66, v58, v66
	v_sub_f32_e32 v67, v59, v67
	v_fmac_f32_e32 v135, v52, v52
	v_sub_f32_e32 v68, v52, v68
	v_sub_f32_e32 v69, v53, v69
	v_fmac_f32_e32 v135, v53, v53
	v_cvt_pk_bf16_f32 v52, v64, v65
	v_cvt_pk_bf16_f32 v53, v66, v67
	ds_read_b128 v[56:59], v84 offset:3072
	ds_read_b128 v[64:67], v84 offset:35840
	v_cvt_pk_bf16_f32 v63, v54, v55
	v_fmac_f32_e32 v135, v54, v54
	s_waitcnt lgkmcnt(1)
	v_mfma_f32_16x16x32_bf16 v[16:19], v[60:63], v[56:59], v[16:19]
	v_lshlrev_b32_e32 v70, 16, v63
	v_and_b32_e32 v71, 0xffff0000, v63
	v_fmac_f32_e32 v135, v55, v55
	v_sub_f32_e32 v70, v54, v70
	v_sub_f32_e32 v71, v55, v71
	v_cvt_pk_bf16_f32 v54, v68, v69
	v_cvt_pk_bf16_f32 v55, v70, v71
	v_fmac_f32_e32 v135, v48, v48
	v_mfma_f32_16x16x32_bf16 v[16:19], v[52:55], v[56:59], v[16:19]
	v_fmac_f32_e32 v135, v49, v49
	v_fmac_f32_e32 v135, v50, v50
	v_cvt_pk_bf16_f32 v52, v48, v49
	v_cvt_pk_bf16_f32 v53, v50, v51
	v_fmac_f32_e32 v135, v51, v51
	v_lshlrev_b32_e32 v56, 16, v52
	v_and_b32_e32 v57, 0xffff0000, v52
	v_lshlrev_b32_e32 v58, 16, v53
	v_and_b32_e32 v59, 0xffff0000, v53
	s_waitcnt lgkmcnt(0)
	v_mfma_f32_16x16x32_bf16 v[16:19], v[60:63], v[64:67], v[16:19]
	v_cvt_pk_bf16_f32 v54, v44, v45
	v_sub_f32_e32 v56, v48, v56
	v_lshlrev_b32_e32 v60, 16, v54
	v_and_b32_e32 v61, 0xffff0000, v54
	v_sub_f32_e32 v57, v49, v57
	v_sub_f32_e32 v58, v50, v58
	v_sub_f32_e32 v59, v51, v59
	v_fmac_f32_e32 v135, v44, v44
	v_sub_f32_e32 v60, v44, v60
	v_sub_f32_e32 v61, v45, v61
	v_fmac_f32_e32 v135, v45, v45
	v_cvt_pk_bf16_f32 v44, v56, v57
	v_cvt_pk_bf16_f32 v45, v58, v59
	ds_read_b128 v[48:51], v84 offset:4096
	ds_read_b128 v[56:59], v84 offset:36864
	v_cvt_pk_bf16_f32 v55, v46, v47
	v_fmac_f32_e32 v135, v46, v46
	s_waitcnt lgkmcnt(1)
	v_mfma_f32_16x16x32_bf16 v[16:19], v[52:55], v[48:51], v[16:19]
	v_lshlrev_b32_e32 v62, 16, v55
	v_and_b32_e32 v63, 0xffff0000, v55
	v_fmac_f32_e32 v135, v47, v47
	v_sub_f32_e32 v62, v46, v62
	v_sub_f32_e32 v63, v47, v63
	v_cvt_pk_bf16_f32 v46, v60, v61
	v_cvt_pk_bf16_f32 v47, v62, v63
	v_fmac_f32_e32 v135, v40, v40
	v_mfma_f32_16x16x32_bf16 v[16:19], v[44:47], v[48:51], v[16:19]
	v_fmac_f32_e32 v135, v41, v41
	v_fmac_f32_e32 v135, v42, v42
	v_cvt_pk_bf16_f32 v44, v40, v41
	v_cvt_pk_bf16_f32 v45, v42, v43
	v_fmac_f32_e32 v135, v43, v43
	v_lshlrev_b32_e32 v48, 16, v44
	v_and_b32_e32 v49, 0xffff0000, v44
	v_lshlrev_b32_e32 v50, 16, v45
	v_and_b32_e32 v51, 0xffff0000, v45
	s_waitcnt lgkmcnt(0)
	v_mfma_f32_16x16x32_bf16 v[16:19], v[52:55], v[56:59], v[16:19]
	v_cvt_pk_bf16_f32 v46, v36, v37
	v_sub_f32_e32 v48, v40, v48
	v_lshlrev_b32_e32 v52, 16, v46
	v_and_b32_e32 v53, 0xffff0000, v46
	v_sub_f32_e32 v49, v41, v49
	v_sub_f32_e32 v50, v42, v50
	v_sub_f32_e32 v51, v43, v51
	v_fmac_f32_e32 v135, v36, v36
	v_sub_f32_e32 v52, v36, v52
	v_sub_f32_e32 v53, v37, v53
	v_fmac_f32_e32 v135, v37, v37
	v_cvt_pk_bf16_f32 v36, v48, v49
	v_cvt_pk_bf16_f32 v37, v50, v51
	ds_read_b128 v[40:43], v84 offset:5120
	ds_read_b128 v[48:51], v84 offset:37888
	v_cvt_pk_bf16_f32 v47, v38, v39
	v_fmac_f32_e32 v135, v38, v38
	s_waitcnt lgkmcnt(1)
	v_mfma_f32_16x16x32_bf16 v[16:19], v[44:47], v[40:43], v[16:19]
	v_lshlrev_b32_e32 v54, 16, v47
	v_and_b32_e32 v55, 0xffff0000, v47
	v_sub_f32_e32 v54, v38, v54
	v_sub_f32_e32 v55, v39, v55
	v_fmac_f32_e32 v135, v39, v39
	v_cvt_pk_bf16_f32 v38, v52, v53
	v_cvt_pk_bf16_f32 v39, v54, v55
	v_fmac_f32_e32 v135, v32, v32
	v_mfma_f32_16x16x32_bf16 v[16:19], v[36:39], v[40:43], v[16:19]
	v_mov_b32_e32 v36, v28
	v_mov_b32_e32 v37, v35
	v_pk_mul_f32 v[42:43], v[30:31], v[30:31]
	v_fmac_f32_e32 v135, v33, v33
	v_pk_mul_f32 v[40:41], v[36:37], v[36:37]
	v_cvt_pk_bf16_f32 v36, v32, v33
	v_fmac_f32_e32 v135, v34, v34
	v_lshlrev_b32_e32 v43, 16, v36
	s_waitcnt lgkmcnt(0)
	v_mfma_f32_16x16x32_bf16 v[16:19], v[44:47], v[48:51], v[16:19]
	v_mul_f32_e64 v44, v28, v28
	v_mul_f32_e64 v45, v29, v29
	v_sub_f32_e32 v43, v32, v43
	v_add_f32_e32 v32, v41, v135
	v_cvt_pk_bf16_f32 v37, v34, v35
	v_cvt_pk_bf16_f32 v39, v30, v31
	v_and_b32_e32 v44, 0xffff0000, v36
	v_lshlrev_b32_e32 v46, 16, v37
	v_and_b32_e32 v47, 0xffff0000, v37
	v_and_b32_e32 v51, 0xffff0000, v39
	v_add_f32_e32 v32, v40, v32
	v_cvt_pk_bf16_f32 v38, v28, v29
	v_lshlrev_b32_e32 v50, 16, v39
	v_lshlrev_b32_e32 v48, 16, v38
	v_sub_f32_e32 v44, v33, v44
	v_sub_f32_e32 v46, v34, v46
	v_sub_f32_e32 v35, v35, v47
	v_sub_f32_e32 v47, v31, v51
	v_add_f32_e32 v32, v45, v32
	v_sub_f32_e32 v28, v28, v48
	v_sub_f32_e32 v30, v30, v50
	v_add_f32_e32 v48, v42, v32
	v_cvt_pk_bf16_f32 v32, v43, v44
	v_cvt_pk_bf16_f32 v33, v46, v35
	v_cvt_pk_bf16_f32 v35, v30, v47
	ds_read_b128 v[40:43], v84 offset:6144
	ds_read_b128 v[44:47], v84 offset:38912
	s_waitcnt lgkmcnt(1)
	v_mfma_f32_16x16x32_bf16 v[16:19], v[36:39], v[40:43], v[16:19]
	v_and_b32_e32 v49, 0xffff0000, v38
	v_sub_f32_e32 v29, v29, v49
	v_cvt_pk_bf16_f32 v34, v28, v29
	v_mov_b32_e32 v30, v24
	v_mfma_f32_16x16x32_bf16 v[16:19], v[32:35], v[40:43], v[16:19]
	v_mul_f32_e64 v32, v30, v30
	v_mul_f32_e64 v33, v31, v31
	v_pk_mul_f32 v[34:35], v[26:27], v[26:27]
	v_mov_b32_e32 v28, v20
	v_mov_b32_e32 v29, v27
	s_waitcnt lgkmcnt(0)
	v_mfma_f32_16x16x32_bf16 v[16:19], v[36:39], v[44:47], v[16:19]
	v_add_f32_e32 v33, v33, v48
	v_pk_mul_f32 v[38:39], v[28:29], v[28:29]
	v_cvt_pk_bf16_f32 v28, v24, v25
	v_cvt_pk_bf16_f32 v30, v20, v21
	v_pk_mul_f32 v[36:37], v[24:25], v[24:25]
	v_lshlrev_b32_e32 v35, 16, v28
	v_lshlrev_b32_e32 v44, 16, v30
	v_pk_mul_f32 v[42:43], v[20:21], v[20:21]
	v_sub_f32_e32 v24, v24, v35
	v_sub_f32_e32 v35, v20, v44
	v_add_f32_e32 v20, v32, v33
	v_add_f32_e32 v20, v37, v20
	v_add_f32_e32 v20, v34, v20
	v_pk_mul_f32 v[40:41], v[22:23], v[22:23]
	v_add_f32_e32 v20, v39, v20
	v_cvt_pk_bf16_f32 v29, v26, v27
	v_and_b32_e32 v36, 0xffff0000, v28
	v_lshlrev_b32_e32 v41, 16, v29
	v_and_b32_e32 v42, 0xffff0000, v29
	v_add_f32_e32 v20, v38, v20
	v_cvt_pk_bf16_f32 v31, v22, v23
	v_and_b32_e32 v45, 0xffff0000, v30
	v_lshlrev_b32_e32 v46, 16, v31
	v_sub_f32_e32 v25, v25, v36
	v_sub_f32_e32 v26, v26, v41
	v_sub_f32_e32 v27, v27, v42
	v_add_f32_e32 v20, v43, v20
	v_sub_f32_e32 v36, v21, v45
	v_sub_f32_e32 v41, v22, v46
	v_add_f32_e32 v135, v40, v20
	v_cvt_pk_bf16_f32 v20, v24, v25
	v_cvt_pk_bf16_f32 v21, v26, v27
	v_cvt_pk_bf16_f32 v22, v35, v36
	ds_read_b128 v[24:27], v84 offset:7168
	ds_read_b128 v[32:35], v84 offset:39936
	s_waitcnt lgkmcnt(1)
	v_mfma_f32_16x16x32_bf16 v[16:19], v[28:31], v[24:27], v[16:19]
	v_and_b32_e32 v47, 0xffff0000, v31
	v_sub_f32_e32 v42, v23, v47
	v_fmac_f32_e32 v135, v23, v23
	v_cvt_pk_bf16_f32 v23, v41, v42
	v_add_u32_e32 v84, 0x2000, v84
	v_mfma_f32_16x16x32_bf16 v[16:19], v[20:23], v[24:27], v[16:19]
	s_waitcnt lgkmcnt(0)
	v_mfma_f32_16x16x32_bf16 v[16:19], v[28:31], v[32:35], v[16:19]
	s_nop 7
	s_nop 7
	ds_write_b128 v231, v[16:19]
	ds_write_b32 v232, v135
	s_waitcnt lgkmcnt(0)
	s_barrier
	ds_read_b128 v[16:19], v233
	ds_read_b128 v[20:23], v233 offset:1280
	ds_read_b128 v[24:27], v233 offset:2560
	ds_read_b128 v[28:31], v233 offset:3840
	ds_read_b32 v135, v234
	ds_read_b32 v32, v234 offset:1280
	ds_read_b32 v33, v234 offset:2560
	ds_read_b32 v34, v234 offset:3840
	s_waitcnt lgkmcnt(0)
	v_pk_add_f32 v[16:17], v[16:17], v[20:21]
	v_pk_add_f32 v[18:19], v[18:19], v[22:23]
	v_pk_add_f32 v[16:17], v[16:17], v[24:25]
	v_pk_add_f32 v[18:19], v[18:19], v[26:27]
	v_pk_add_f32 v[16:17], v[16:17], v[28:29]
	v_pk_add_f32 v[18:19], v[18:19], v[30:31]
	v_add_f32_e32 v135, v135, v32
	v_add_f32_e32 v135, v135, v33
	v_add_f32_e32 v135, v135, v34
	v_and_b32_e32 v24, 64, v133
	v_xor_b32_e32 v20, 16, v133
	v_add_u32_e32 v21, 64, v24
	v_cmp_lt_i32_e32 vcc, v20, v21
	v_xor_b32_e32 v22, 32, v133
	s_mov_b32 s0, 0x800000
	v_cndmask_b32_e32 v20, v133, v20, vcc
	v_lshlrev_b32_e32 v20, 2, v20
	ds_bpermute_b32 v20, v20, v135
	v_cmp_lt_i32_e32 vcc, v22, v21
	v_or_b32_e32 v25, v24, v122
	v_lshlrev_b32_e32 v25, 2, v25
	v_cndmask_b32_e32 v22, v133, v22, vcc
	s_waitcnt lgkmcnt(0)
	v_add_f32_e32 v20, v135, v20
	v_lshlrev_b32_e32 v22, 2, v22
	ds_bpermute_b32 v22, v22, v20
	v_xor_b32_e32 v23, 1, v133
	v_or_b32_e32 v28, v24, v123
	s_add_i32 s84, s62, s50
	s_mov_b32 s85, -4
	s_waitcnt lgkmcnt(0)
	v_add_f32_e32 v20, v20, v22
	v_fmamk_f32 v20, v20, 0x3a800000, v132
	v_mul_f32_e32 v22, 0x4b800000, v20
	v_cmp_gt_f32_e32 vcc, s0, v20
	s_or_b32 s0, s51, s61
	s_lshl_b32 s0, s0, 4
	v_cndmask_b32_e32 v20, v20, v22, vcc
	v_rsq_f32_e32 v20, v20
	v_xor_b32_e32 v22, 2, v133
	s_add_i32 s0, s0, s33
	s_and_b32 s0, s0, 0xff0
	v_mul_f32_e32 v26, 0x45800000, v20
	v_cndmask_b32_e32 v64, v20, v26, vcc
	ds_bpermute_b32 v20, v25, v64
	v_cmp_lt_i32_e32 vcc, v23, v21
	v_xor_b32_e32 v25, 4, v133
	v_or_b32_e32 v30, s0, v122
	v_cndmask_b32_e32 v23, v133, v23, vcc
	v_lshlrev_b32_e32 v26, 2, v23
	s_waitcnt lgkmcnt(0)
	v_fma_f32 v16, v16, v20, v99
	ds_bpermute_b32 v20, v26, v16
	v_cmp_lt_i32_e32 vcc, v22, v21
	v_xor_b32_e32 v23, 8, v133
	v_lshlrev_b32_e32 v84, 2, v30
	v_cndmask_b32_e32 v22, v133, v22, vcc
	s_waitcnt lgkmcnt(0)
	v_max_f32_e32 v20, v20, v20
	v_lshlrev_b32_e32 v27, 2, v22
	v_max_f32_e32 v20, v16, v20
	ds_bpermute_b32 v22, v27, v20
	v_cmp_lt_i32_e32 vcc, v25, v21
	s_waitcnt lgkmcnt(0)
	v_max_f32_e32 v22, v22, v22
	v_cndmask_b32_e32 v25, v133, v25, vcc
	v_lshlrev_b32_e32 v29, 2, v25
	v_max_f32_e32 v20, v20, v22
	ds_bpermute_b32 v22, v29, v20
	v_lshlrev_b32_e32 v25, 2, v28
	ds_bpermute_b32 v25, v25, v64
	v_cmp_lt_i32_e32 vcc, v23, v21
	s_waitcnt lgkmcnt(0)
	v_fma_f32 v17, v17, v25, v99
	v_cndmask_b32_e32 v21, v133, v23, vcc
	v_lshlrev_b32_e32 v28, 2, v21
	v_max_f32_e32 v21, v22, v22
	v_max_f32_e32 v20, v20, v21
	ds_bpermute_b32 v22, v28, v20
	ds_bpermute_b32 v21, v26, v17
	s_waitcnt lgkmcnt(1)
	v_max_f32_e32 v22, v22, v22
	s_waitcnt lgkmcnt(0)
	v_max_f32_e32 v21, v21, v21
	v_max_f32_e32 v20, v20, v22
	v_sub_f32_e32 v16, v16, v20
	v_max_f32_e32 v20, v17, v21
	ds_bpermute_b32 v21, v27, v20
	v_mul_f32_e32 v22, 0x3fb8aa3b, v16
	v_fma_f32 v23, v16, s91, -v22
	v_rndne_f32_e32 v25, v22
	v_fmac_f32_e32 v23, 0x32a5705f, v16
	s_waitcnt lgkmcnt(0)
	v_max_f32_e32 v21, v21, v21
	v_max_f32_e32 v20, v20, v21
	ds_bpermute_b32 v21, v29, v20
	v_sub_f32_e32 v22, v22, v25
	v_add_f32_e32 v22, v22, v23
	v_exp_f32_e32 v22, v22
	v_cvt_i32_f32_e32 v23, v25
	s_waitcnt lgkmcnt(0)
	v_max_f32_e32 v21, v21, v21
	v_max_f32_e32 v20, v20, v21
	ds_bpermute_b32 v21, v28, v20
	v_ldexp_f32 v22, v22, v23
	v_cmp_ngt_f32_e32 vcc, s92, v16
	s_waitcnt lgkmcnt(0)
	v_max_f32_e32 v21, v21, v21
	v_max_f32_e32 v20, v20, v21
	v_sub_f32_e32 v17, v17, v20
	v_mul_f32_e32 v20, 0x3fb8aa3b, v17
	v_fma_f32 v21, v17, s91, -v20
	v_rndne_f32_e32 v23, v20
	v_fmac_f32_e32 v21, 0x32a5705f, v17
	v_sub_f32_e32 v20, v20, v23
	v_add_f32_e32 v20, v20, v21
	v_exp_f32_e32 v21, v20
	v_cvt_i32_f32_e32 v23, v23
	v_cndmask_b32_e32 v22, 0, v22, vcc
	v_cmp_nlt_f32_e32 vcc, s93, v16
	v_ldexp_f32 v21, v21, v23
	s_nop 0
	v_cndmask_b32_e32 v16, v134, v22, vcc
	v_cmp_ngt_f32_e32 vcc, s92, v17
	ds_bpermute_b32 v20, v26, v16
	s_nop 0
	v_cndmask_b32_e32 v21, 0, v21, vcc
	v_cmp_nlt_f32_e32 vcc, s93, v17
	s_nop 1
	v_cndmask_b32_e32 v17, v134, v21, vcc
	ds_bpermute_b32 v21, v26, v17
	s_waitcnt lgkmcnt(0)
	v_pk_add_f32 v[20:21], v[16:17], v[20:21]
	ds_bpermute_b32 v22, v27, v20
	ds_bpermute_b32 v23, v27, v21
	s_waitcnt lgkmcnt(0)
	v_pk_add_f32 v[20:21], v[20:21], v[22:23]
	v_or_b32_e32 v22, v24, v124
	v_lshlrev_b32_e32 v22, 2, v22
	ds_bpermute_b32 v25, v22, v64
	ds_bpermute_b32 v22, v29, v20
	ds_bpermute_b32 v23, v29, v21
	v_or_b32_e32 v24, v24, v125
	v_lshlrev_b32_e32 v24, 2, v24
	s_waitcnt lgkmcnt(2)
	v_fma_f32 v18, v18, v25, v99
	ds_bpermute_b32 v25, v26, v18
	s_waitcnt lgkmcnt(1)
	v_pk_add_f32 v[20:21], v[20:21], v[22:23]
	ds_bpermute_b32 v22, v28, v20
	ds_bpermute_b32 v23, v28, v21
	ds_bpermute_b32 v24, v24, v64
	s_waitcnt lgkmcnt(3)
	v_max_f32_e32 v25, v25, v25
	v_max_f32_e32 v25, v18, v25
	ds_bpermute_b32 v31, v27, v25
	s_waitcnt lgkmcnt(2)
	v_pk_add_f32 v[20:21], v[20:21], v[22:23]
	s_waitcnt lgkmcnt(1)
	v_fma_f32 v19, v19, v24, v99
	v_div_scale_f32 v32, s[0:1], v21, v21, v17
	s_waitcnt lgkmcnt(0)
	v_max_f32_e32 v22, v31, v31
	v_max_f32_e32 v25, v25, v22
	v_rcp_f32_e32 v33, v32
	ds_bpermute_b32 v31, v29, v25
	ds_bpermute_b32 v24, v26, v19
	v_lshl_add_u64 v[22:23], v[116:117], 0, v[84:85]
	v_fma_f32 v30, -v32, v33, 1.0
	v_fmac_f32_e32 v33, v30, v33
	s_waitcnt lgkmcnt(1)
	v_max_f32_e32 v30, v31, v31
	v_max_f32_e32 v25, v25, v30
	ds_bpermute_b32 v30, v28, v25
	s_waitcnt lgkmcnt(1)
	v_max_f32_e32 v24, v24, v24
	v_max_f32_e32 v24, v19, v24
	v_div_scale_f32 v31, vcc, v17, v21, v17
	s_waitcnt lgkmcnt(0)
	v_max_f32_e32 v30, v30, v30
	v_max_f32_e32 v25, v25, v30
	v_sub_f32_e32 v18, v18, v25
	ds_bpermute_b32 v25, v27, v24
	v_mul_f32_e32 v30, 0x3fb8aa3b, v18
	v_fma_f32 v35, v18, s91, -v30
	v_rndne_f32_e32 v36, v30
	v_fmac_f32_e32 v35, 0x32a5705f, v18
	s_waitcnt lgkmcnt(0)
	v_max_f32_e32 v25, v25, v25
	v_max_f32_e32 v24, v24, v25
	ds_bpermute_b32 v25, v29, v24
	v_sub_f32_e32 v30, v30, v36
	v_add_f32_e32 v30, v30, v35
	v_exp_f32_e32 v30, v30
	v_cvt_i32_f32_e32 v35, v36
	s_waitcnt lgkmcnt(0)
	v_max_f32_e32 v25, v25, v25
	v_max_f32_e32 v24, v24, v25
	ds_bpermute_b32 v25, v28, v24
	v_ldexp_f32 v30, v30, v35
	v_cmp_ngt_f32_e64 s[0:1], s92, v18
	v_mul_f32_e32 v34, v31, v33
	v_fma_f32 v36, -v32, v34, v31
	s_waitcnt lgkmcnt(0)
	v_max_f32_e32 v25, v25, v25
	v_max_f32_e32 v24, v24, v25
	v_sub_f32_e32 v19, v19, v24
	v_mul_f32_e32 v24, 0x3fb8aa3b, v19
	v_fma_f32 v25, v19, s91, -v24
	v_rndne_f32_e32 v35, v24
	v_fmac_f32_e32 v25, 0x32a5705f, v19
	v_sub_f32_e32 v24, v24, v35
	v_add_f32_e32 v24, v24, v25
	v_exp_f32_e32 v25, v24
	v_cvt_i32_f32_e32 v35, v35
	v_cndmask_b32_e64 v30, 0, v30, s[0:1]
	v_cmp_nlt_f32_e64 s[0:1], s93, v18
	v_fmac_f32_e32 v34, v36, v33
	v_ldexp_f32 v25, v25, v35
	v_cndmask_b32_e64 v18, v134, v30, s[0:1]
	v_cmp_ngt_f32_e64 s[0:1], s92, v19
	ds_bpermute_b32 v24, v26, v18
	s_nop 0
	v_cndmask_b32_e64 v25, 0, v25, s[0:1]
	v_cmp_nlt_f32_e64 s[0:1], s93, v19
	s_nop 1
	v_cndmask_b32_e64 v19, v134, v25, s[0:1]
	ds_bpermute_b32 v25, v26, v19
	v_fma_f32 v26, -v32, v34, v31
	v_div_fmas_f32 v30, v26, v33, v34
	v_div_fixup_f32 v17, v30, v21, v17
	v_div_scale_f32 v21, s[0:1], v20, v20, v16
	s_waitcnt lgkmcnt(0)
	v_pk_add_f32 v[24:25], v[18:19], v[24:25]
	ds_bpermute_b32 v26, v27, v24
	ds_bpermute_b32 v27, v27, v25
	v_rcp_f32_e32 v30, v21
	s_waitcnt lgkmcnt(0)
	v_pk_add_f32 v[24:25], v[24:25], v[26:27]
	ds_bpermute_b32 v26, v29, v24
	ds_bpermute_b32 v27, v29, v25
	v_fma_f32 v29, -v21, v30, 1.0
	v_fmac_f32_e32 v30, v29, v30
	v_div_scale_f32 v29, vcc, v16, v20, v16
	s_waitcnt lgkmcnt(0)
	v_pk_add_f32 v[24:25], v[24:25], v[26:27]
	ds_bpermute_b32 v26, v28, v24
	ds_bpermute_b32 v27, v28, v25
	v_mul_f32_e32 v28, v29, v30
	v_fma_f32 v31, -v21, v28, v29
	v_fmac_f32_e32 v28, v31, v30
	v_fma_f32 v21, -v21, v28, v29
	s_waitcnt lgkmcnt(0)
	v_pk_add_f32 v[24:25], v[24:25], v[26:27]
	v_div_fmas_f32 v21, v21, v30, v28
	v_div_scale_f32 v26, s[0:1], v25, v25, v19
	v_rcp_f32_e32 v27, v26
	v_div_fixup_f32 v16, v21, v20, v16
	v_fma_f32 v20, -v26, v27, 1.0
	v_fmac_f32_e32 v27, v20, v27
	v_div_scale_f32 v20, vcc, v19, v25, v19
	v_mul_f32_e32 v21, v20, v27
	v_fma_f32 v28, -v26, v21, v20
	v_fmac_f32_e32 v21, v28, v27
	v_fma_f32 v20, -v26, v21, v20
	v_div_scale_f32 v26, s[0:1], v24, v24, v18
	v_rcp_f32_e32 v28, v26
	v_div_fmas_f32 v20, v20, v27, v21
	v_div_fixup_f32 v19, v20, v25, v19
	v_fma_f32 v20, -v26, v28, 1.0
	v_fmac_f32_e32 v28, v20, v28
	v_div_scale_f32 v20, vcc, v18, v24, v18
	v_mul_f32_e32 v21, v20, v28
	v_fma_f32 v25, -v26, v21, v20
	v_fmac_f32_e32 v21, v25, v28
	v_fma_f32 v20, -v26, v21, v20
	v_div_fmas_f32 v20, v20, v28, v21
	v_div_fixup_f32 v18, v20, v24, v18
	global_store_dwordx4 v[22:23], v[16:19], off
	s_nop 1
	v_lshlrev_b32_e32 v16, 2, v133
	v_and_b32_e32 v65, 0x100, v16
	ds_read_b128 v[242:245], v230 offset:0
	ds_read_b128 v[246:249], v230 offset:16
	ds_read_b128 v[250:253], v230 offset:4096
	ds_read_b128 v[180:183], v230 offset:4112
	s_waitcnt lgkmcnt(0)
	v_pk_mul_f32 v[184:185], v[152:153], v[64:65] op_sel_hi:[1,0]
	v_pk_mul_f32 v[186:187], v[154:155], v[64:65] op_sel_hi:[1,0]
	v_pk_mul_f32 v[188:189], v[148:149], v[64:65] op_sel_hi:[1,0]
	v_pk_mul_f32 v[190:191], v[150:151], v[64:65] op_sel_hi:[1,0]
	v_pk_fma_f32 v[184:185], v[242:243], v[184:185], v[250:251]
	v_pk_fma_f32 v[186:187], v[244:245], v[186:187], v[252:253]
	v_pk_fma_f32 v[188:189], v[246:247], v[188:189], v[180:181]
	v_pk_fma_f32 v[190:191], v[248:249], v[190:191], v[182:183]
	v_cvt_pk_bf16_f32 v184, v184, v185
	v_cvt_pk_bf16_f32 v185, v186, v187
	v_cvt_pk_bf16_f32 v186, v188, v189
	v_cvt_pk_bf16_f32 v187, v190, v191
	global_store_dwordx4 v[238:239], v[184:187], off offset:0
	ds_read_b128 v[242:245], v230 offset:128
	ds_read_b128 v[246:249], v230 offset:144
	ds_read_b128 v[250:253], v230 offset:4224
	ds_read_b128 v[180:183], v230 offset:4240
	s_waitcnt lgkmcnt(0)
	v_pk_mul_f32 v[184:185], v[160:161], v[64:65] op_sel_hi:[1,0]
	v_pk_mul_f32 v[186:187], v[162:163], v[64:65] op_sel_hi:[1,0]
	v_pk_mul_f32 v[188:189], v[156:157], v[64:65] op_sel_hi:[1,0]
	v_pk_mul_f32 v[190:191], v[158:159], v[64:65] op_sel_hi:[1,0]
	v_pk_fma_f32 v[184:185], v[242:243], v[184:185], v[250:251]
	v_pk_fma_f32 v[186:187], v[244:245], v[186:187], v[252:253]
	v_pk_fma_f32 v[188:189], v[246:247], v[188:189], v[180:181]
	v_pk_fma_f32 v[190:191], v[248:249], v[190:191], v[182:183]
	v_cvt_pk_bf16_f32 v184, v184, v185
	v_cvt_pk_bf16_f32 v185, v186, v187
	v_cvt_pk_bf16_f32 v186, v188, v189
	v_cvt_pk_bf16_f32 v187, v190, v191
	global_store_dwordx4 v[238:239], v[184:187], off offset:64
	ds_read_b128 v[242:245], v230 offset:256
	ds_read_b128 v[246:249], v230 offset:272
	ds_read_b128 v[250:253], v230 offset:4352
	ds_read_b128 v[180:183], v230 offset:4368
	s_waitcnt lgkmcnt(0)
	v_pk_mul_f32 v[184:185], v[168:169], v[64:65] op_sel_hi:[1,0]
	v_pk_mul_f32 v[186:187], v[170:171], v[64:65] op_sel_hi:[1,0]
	v_pk_mul_f32 v[188:189], v[164:165], v[64:65] op_sel_hi:[1,0]
	v_pk_mul_f32 v[190:191], v[166:167], v[64:65] op_sel_hi:[1,0]
	v_pk_fma_f32 v[184:185], v[242:243], v[184:185], v[250:251]
	v_pk_fma_f32 v[186:187], v[244:245], v[186:187], v[252:253]
	v_pk_fma_f32 v[188:189], v[246:247], v[188:189], v[180:181]
	v_pk_fma_f32 v[190:191], v[248:249], v[190:191], v[182:183]
	v_cvt_pk_bf16_f32 v184, v184, v185
	v_cvt_pk_bf16_f32 v185, v186, v187
	v_cvt_pk_bf16_f32 v186, v188, v189
	v_cvt_pk_bf16_f32 v187, v190, v191
	global_store_dwordx4 v[238:239], v[184:187], off offset:128
	ds_read_b128 v[242:245], v230 offset:384
	ds_read_b128 v[246:249], v230 offset:400
	ds_read_b128 v[250:253], v230 offset:4480
	ds_read_b128 v[180:183], v230 offset:4496
	s_waitcnt lgkmcnt(0)
	v_pk_mul_f32 v[184:185], v[176:177], v[64:65] op_sel_hi:[1,0]
	v_pk_mul_f32 v[186:187], v[178:179], v[64:65] op_sel_hi:[1,0]
	v_pk_mul_f32 v[188:189], v[172:173], v[64:65] op_sel_hi:[1,0]
	v_pk_mul_f32 v[190:191], v[174:175], v[64:65] op_sel_hi:[1,0]
	v_pk_fma_f32 v[184:185], v[242:243], v[184:185], v[250:251]
	v_pk_fma_f32 v[186:187], v[244:245], v[186:187], v[252:253]
	v_pk_fma_f32 v[188:189], v[246:247], v[188:189], v[180:181]
	v_pk_fma_f32 v[190:191], v[248:249], v[190:191], v[182:183]
	v_cvt_pk_bf16_f32 v184, v184, v185
	v_cvt_pk_bf16_f32 v185, v186, v187
	v_cvt_pk_bf16_f32 v186, v188, v189
	v_cvt_pk_bf16_f32 v187, v190, v191
	global_store_dwordx4 v[238:239], v[184:187], off offset:192
	ds_read_b128 v[242:245], v230 offset:512
	ds_read_b128 v[246:249], v230 offset:528
	ds_read_b128 v[250:253], v230 offset:4608
	ds_read_b128 v[180:183], v230 offset:4624
	s_waitcnt lgkmcnt(0)
	v_pk_mul_f32 v[184:185], v[200:201], v[64:65] op_sel_hi:[1,0]
	v_pk_mul_f32 v[186:187], v[202:203], v[64:65] op_sel_hi:[1,0]
	v_pk_mul_f32 v[188:189], v[196:197], v[64:65] op_sel_hi:[1,0]
	v_pk_mul_f32 v[190:191], v[198:199], v[64:65] op_sel_hi:[1,0]
	v_pk_fma_f32 v[184:185], v[242:243], v[184:185], v[250:251]
	v_pk_fma_f32 v[186:187], v[244:245], v[186:187], v[252:253]
	v_pk_fma_f32 v[188:189], v[246:247], v[188:189], v[180:181]
	v_pk_fma_f32 v[190:191], v[248:249], v[190:191], v[182:183]
	v_cvt_pk_bf16_f32 v184, v184, v185
	v_cvt_pk_bf16_f32 v185, v186, v187
	v_cvt_pk_bf16_f32 v186, v188, v189
	v_cvt_pk_bf16_f32 v187, v190, v191
	global_store_dwordx4 v[238:239], v[184:187], off offset:256
	ds_read_b128 v[242:245], v230 offset:640
	ds_read_b128 v[246:249], v230 offset:656
	ds_read_b128 v[250:253], v230 offset:4736
	ds_read_b128 v[180:183], v230 offset:4752
	s_waitcnt lgkmcnt(0)
	v_pk_mul_f32 v[184:185], v[208:209], v[64:65] op_sel_hi:[1,0]
	v_pk_mul_f32 v[186:187], v[210:211], v[64:65] op_sel_hi:[1,0]
	v_pk_mul_f32 v[188:189], v[204:205], v[64:65] op_sel_hi:[1,0]
	v_pk_mul_f32 v[190:191], v[206:207], v[64:65] op_sel_hi:[1,0]
	v_pk_fma_f32 v[184:185], v[242:243], v[184:185], v[250:251]
	v_pk_fma_f32 v[186:187], v[244:245], v[186:187], v[252:253]
	v_pk_fma_f32 v[188:189], v[246:247], v[188:189], v[180:181]
	v_pk_fma_f32 v[190:191], v[248:249], v[190:191], v[182:183]
	v_cvt_pk_bf16_f32 v184, v184, v185
	v_cvt_pk_bf16_f32 v185, v186, v187
	v_cvt_pk_bf16_f32 v186, v188, v189
	v_cvt_pk_bf16_f32 v187, v190, v191
	global_store_dwordx4 v[238:239], v[184:187], off offset:320
	ds_read_b128 v[242:245], v230 offset:768
	ds_read_b128 v[246:249], v230 offset:784
	ds_read_b128 v[250:253], v230 offset:4864
	ds_read_b128 v[180:183], v230 offset:4880
	s_waitcnt lgkmcnt(0)
	v_pk_mul_f32 v[184:185], v[212:213], v[64:65] op_sel_hi:[1,0]
	v_pk_mul_f32 v[186:187], v[214:215], v[64:65] op_sel_hi:[1,0]
	v_pk_mul_f32 v[188:189], v[216:217], v[64:65] op_sel_hi:[1,0]
	v_pk_mul_f32 v[190:191], v[218:219], v[64:65] op_sel_hi:[1,0]
	v_pk_fma_f32 v[184:185], v[242:243], v[184:185], v[250:251]
	v_pk_fma_f32 v[186:187], v[244:245], v[186:187], v[252:253]
	v_pk_fma_f32 v[188:189], v[246:247], v[188:189], v[180:181]
	v_pk_fma_f32 v[190:191], v[248:249], v[190:191], v[182:183]
	v_cvt_pk_bf16_f32 v184, v184, v185
	v_cvt_pk_bf16_f32 v185, v186, v187
	v_cvt_pk_bf16_f32 v186, v188, v189
	v_cvt_pk_bf16_f32 v187, v190, v191
	global_store_dwordx4 v[238:239], v[184:187], off offset:384
	ds_read_b128 v[242:245], v230 offset:896
	ds_read_b128 v[246:249], v230 offset:912
	ds_read_b128 v[250:253], v230 offset:4992
	ds_read_b128 v[180:183], v230 offset:5008
	s_waitcnt lgkmcnt(0)
	v_pk_mul_f32 v[184:185], v[224:225], v[64:65] op_sel_hi:[1,0]
	v_pk_mul_f32 v[186:187], v[226:227], v[64:65] op_sel_hi:[1,0]
	v_pk_mul_f32 v[188:189], v[220:221], v[64:65] op_sel_hi:[1,0]
	v_pk_mul_f32 v[190:191], v[222:223], v[64:65] op_sel_hi:[1,0]
	v_pk_fma_f32 v[184:185], v[242:243], v[184:185], v[250:251]
	v_pk_fma_f32 v[186:187], v[244:245], v[186:187], v[252:253]
	v_pk_fma_f32 v[188:189], v[246:247], v[188:189], v[180:181]
	v_pk_fma_f32 v[190:191], v[248:249], v[190:191], v[182:183]
	v_cvt_pk_bf16_f32 v184, v184, v185
	v_cvt_pk_bf16_f32 v185, v186, v187
	v_cvt_pk_bf16_f32 v186, v188, v189
	v_cvt_pk_bf16_f32 v187, v190, v191
	global_store_dwordx4 v[238:239], v[184:187], off offset:448
	v_xor_b32_e32 v231, 0x8000, v231
	v_xor_b32_e32 v232, 0x8000, v232
	v_xor_b32_e32 v233, 0x8000, v233
	v_xor_b32_e32 v234, 0x8000, v234
	s_add_i32 s98, s98, 1
	s_cmp_lt_u32 s98, 8
	s_cbranch_scc1 .Lp5n_loop
	s_lshl_b32 s61, s100, 2
	s_add_i32 s61, s61, s99
	s_lshl_b32 s61, s61, 1
	s_lshl_b32 s62, s61, 4
	s_lshl_b32 s101, s94, 8
	s_add_i32 s62, s62, s101
	v_or_b32_e32 v130, s62, v120
	s_add_i32 s94, s94, s82
	s_add_i32 s62, s62, s63
	s_cmpk_gt_i32 s94, 0xff
	v_add_u32_e32 v130, s63, v130
	s_cbranch_scc0 .LBB0_738
